# dn_chunk_prep: wave 0's dg/dbeta loads issued before the q/k/v tile loads instead of after their last wait
# baseline (speedup 1.0000x reference)
.LBB0_573:
	s_andn2_b64 vcc, exec, s[0:1]
	s_cbranch_vccnz .LBB0_341
	v_mov_b32_e32 v74, v139
	s_lshl_b32 s8, s66, 3
	s_movk_i32 s0, 0x200
	s_and_b32 s6, s66, 1
	s_bfe_u32 s7, s66, 0x20001
	s_andn2_b32 s8, s8, 63
	s_mov_b64 s[98:99], exec
	v_cmp_gt_u32_e32 vcc, 64, v74
	s_and_b64 exec, exec, vcc
	s_cmp_eq_u32 s6, 0
	v_xor_b32_e32 v228, 63, v74
	s_cselect_b64 vcc, -1, 0
	v_cndmask_b32_e32 v228, v228, v74, vcc
	v_or_b32_e32 v228, s8, v228
	v_ashrrev_i32_e32 v229, 31, v228
	v_lshlrev_b64 v[228:229], 3, v[228:229]
	v_lshl_or_b32 v228, s6, 2, v228
	v_or_b32_e32 v228, s7, v228
	v_lshlrev_b64 v[228:229], 2, v[228:229]
	v_lshl_add_u64 v[230:231], s[86:87], 0, v[228:229]
	global_load_dword v232, v[230:231], off
	v_lshl_add_u64 v[228:229], s[84:85], 0, v[228:229]
	global_load_dword v233, v[228:229], off
	s_mov_b64 exec, s[98:99]
	v_cmp_gt_i32_e32 vcc, s0, v74
	s_and_saveexec_b64 s[2:3], vcc
	s_movk_i32 s9, 0xff
	s_movk_i32 s12, 0x90
	s_cbranch_execz .LBB0_577
	s_cmp_eq_u32 s6, 0
	s_cselect_b64 s[0:1], -1, 0
	s_lshl_b32 s4, s7, 6
	v_and_b32_e32 v1, 7, v74
	v_lshl_or_b32 v0, v1, 3, s4
	v_lshlrev_b32_e32 v2, 4, v1
	s_mov_b64 s[4:5], 0
	s_mov_b32 s38, 0x4000
	s_mov_b32 s39, 0
	s_cmp_eq_u32 s6, 0
	s_cbranch_scc1 .Ldn_ld_fwd
	s_mov_b32 s38, 0xffffc000
	s_mov_b32 s39, -1

.LBB0_577:
	s_or_b64 exec, exec, s[2:3]
	v_and_b32_e32 v75, 63, v74
	v_cmp_gt_u32_e64 s[0:1], 64, v74
	v_lshlrev_b32_e32 v77, 2, v75
	s_and_saveexec_b64 s[2:3], s[0:1]
	s_cbranch_execz .LBB0_579
	s_cmp_eq_u32 s6, 0
	v_xor_b32_e32 v0, 63, v74
	s_cselect_b64 s[0:1], -1, 0
	v_cndmask_b32_e64 v0, v0, v74, s[0:1]
	v_or_b32_e32 v0, s8, v0
	v_ashrrev_i32_e32 v1, 31, v0
	v_lshlrev_b64 v[0:1], 3, v[0:1]
	v_lshl_or_b32 v0, s6, 2, v0
	v_or_b32_e32 v0, s7, v0
	v_lshlrev_b64 v[0:1], 2, v[0:1]
	s_waitcnt vmcnt(0)
	v_mov_b32_e32 v2, v232
	v_mov_b32_e32 v0, v233
	v_add_u32_e32 v1, -1, v176
	v_cmp_lt_i32_e64 s[0:1], v1, v177
	v_add_u32_e32 v3, -2, v176
	s_nop 0
	v_cndmask_b32_e64 v1, v1, v176, s[0:1]
	v_lshlrev_b32_e32 v1, 2, v1
	v_cmp_lt_i32_e64 s[0:1], v3, v177
	s_waitcnt vmcnt(1)
	ds_bpermute_b32 v1, v1, v2
	v_cndmask_b32_e64 v3, v3, v176, s[0:1]
	v_cmp_eq_u32_e64 s[0:1], 0, v75
	v_lshlrev_b32_e32 v3, 2, v3
	s_waitcnt lgkmcnt(0)
	v_add_f32_e32 v1, v2, v1
	v_cndmask_b32_e64 v1, v1, v2, s[0:1]
	ds_bpermute_b32 v2, v3, v1
	v_add_u32_e32 v3, -4, v176
	v_cmp_lt_i32_e64 s[0:1], v3, v177
	s_waitcnt lgkmcnt(0)
	v_add_f32_e32 v2, v1, v2
	v_cndmask_b32_e64 v3, v3, v176, s[0:1]
	v_cmp_gt_u32_e64 s[0:1], 2, v75
	v_lshlrev_b32_e32 v3, 2, v3
	s_nop 0
	v_cndmask_b32_e64 v1, v2, v1, s[0:1]
	ds_bpermute_b32 v2, v3, v1
	v_add_u32_e32 v3, -8, v176
	v_cmp_lt_i32_e64 s[0:1], v3, v177
	s_waitcnt lgkmcnt(0)
	v_add_f32_e32 v2, v1, v2
	v_cndmask_b32_e64 v3, v3, v176, s[0:1]
	v_cmp_gt_u32_e64 s[0:1], 4, v75
	v_lshlrev_b32_e32 v3, 2, v3
	s_nop 0
	v_cndmask_b32_e64 v1, v2, v1, s[0:1]
	ds_bpermute_b32 v2, v3, v1
	v_add_u32_e32 v3, -16, v176
	v_cmp_lt_i32_e64 s[0:1], v3, v177
	s_waitcnt lgkmcnt(0)
	v_add_f32_e32 v2, v1, v2
	v_cndmask_b32_e64 v3, v3, v176, s[0:1]
	v_cmp_gt_u32_e64 s[0:1], 8, v75
	v_lshlrev_b32_e32 v3, 2, v3
	s_nop 0
	v_cndmask_b32_e64 v1, v2, v1, s[0:1]
	ds_bpermute_b32 v2, v3, v1
	v_subrev_u32_e32 v3, 32, v176
	v_cmp_lt_i32_e64 s[0:1], v3, v177
	s_waitcnt lgkmcnt(0)
	v_add_f32_e32 v2, v1, v2
	v_cndmask_b32_e64 v3, v3, v176, s[0:1]
	v_cmp_gt_u32_e64 s[0:1], 16, v75
	v_lshlrev_b32_e32 v3, 2, v3
	s_nop 0
	v_cndmask_b32_e64 v1, v2, v1, s[0:1]
	ds_bpermute_b32 v2, v3, v1
	v_cmp_gt_u32_e64 s[0:1], 32, v75
	s_waitcnt lgkmcnt(0)
	v_add_f32_e32 v2, v1, v2
	v_cndmask_b32_e64 v1, v2, v1, s[0:1]
	s_waitcnt vmcnt(0)
	ds_write2st64_b32 v77, v1, v0 offset0:236 offset1:237
